# static s_setprio 1 for waves 4-7 inside the diff-attention main loop (younger half priority raise), timing-only
# speedup vs baseline: 1.0059x; 1.0059x over previous
; template <int MODE>
; __device__ __forceinline__ void attn_unit(bf16r* P0, const bf16r* __restrict__ PKV, int rowbase, int seqL, int h, int blk, float lam,
;                                           const float* __restrict__ subg, const float* __restrict__ tsrc, char* lds) {
;     ...
;     for (int j = 1; j + 1 < NH; j += 2) {
;       STEP(pB0, pB1, mnB, alB, pA0, pA1, alA, j);
;       STEP(pA0, pA1, mnA, alA, pB0, pB1, alB, j + 1);
.LBB0_215:
	s_cmp_lt_u32 s32, 0x100
	s_cbranch_scc1 .Lstag_a
	s_setprio 1
